# merged 64-MFMA slots in P8 K-loop, role-split DMA staging (lead 2 slots)
# baseline (speedup 1.0000x reference)
;     __host__ __device__ bool next(int i, Unit& u) const { const int L = i * G + c; if (L >= n) return false; u.pm = L; u.pn = L >> 2; return true; }
; #define PG8_STAGE(bufoff, gbase, voff) do { _Pragma("unroll") for (int _i = 0; _i < 2; ++_i) \
;         __builtin_amdgcn_global_load_lds((const unsigned*)((const char*)(gbase) + (voff)[_i]), (PG8_LAS unsigned*)(lds + (bufoff) + ldsw + _i * 8192), 16, 0, 0); } while (0)
; #define PG8_WAIT_V(n) asm volatile("s_waitcnt vmcnt(" #n ")" ::: "memory")
; #define PG8_BAR __builtin_amdgcn_s_barrier()
; template <class Epi, class Sched, bool ALIGN_EPI>
; __device__ __forceinline__ void gemm_phase(PG8_LAS unsigned char* lds, const Gemm g, const Sched& S, const Epi& E) {
;     ...
;     const unsigned ldsw = (unsigned)wid * 1024u;
;     const size_t tailoff = (size_t)(nt - 2) * (size_t)(BK * 2), tailoffA = (size_t)(nt - 2) * kstepA;
;     const int aoff = lds_byte(wr * 64 + fr, fq * 8), boff = lds_byte(wc * 32 + fr, fq * 8);
;     ...
;     Unit cur, nxt; int ui = 0;
;     if (!S.next(0, cur)) return;
;     f32x4 acc[2][2][4][2];
; #pragma unroll
;     for (int a = 0; a < 2; ++a)
; #pragma unroll
;         for (int b = 0; b < 2; ++b)
; #pragma unroll
;             for (int m = 0; m < 4; ++m)
; #pragma unroll
;                 for (int n = 0; n < 2; ++n) acc[a][b][m][n] = (f32x4){0.f, 0.f, 0.f, 0.f};
;     bf16x8 At[4][2], B0[2][2], B1[2][2];
;     const char* cA = (const char*)g.A + (size_t)cur.pm * tstepA; const char* cB = (const char*)g.Bt + (size_t)cur.pn * tstepB;
;     PG8_STAGE(PG8_SB(0, 0), cB, voffB); PG8_STAGE(PG8_SB(0, 1), cB + hstepB, voffB); PG8_STAGE(PG8_SA(0, 0), cA, voffA); PG8_STAGE(PG8_SA(0, 1), cA + hstepA, voffA);
;     if (wr == 1) PG8_BAR;
;     PG8_WAIT_V(2); PG8_BAR;
;     PG8_STAGE(PG8_SB(1, 0), cB + kstep, voffB); PG8_STAGE(PG8_SA(1, 0), cA + kstepA, voffA); PG8_STAGE(PG8_SB(1, 1), cB + hstepB + kstep, voffB);
;     PG8_WAIT_V(6); PG8_BAR;
.LBB0_895:
	s_lshl_b32 s5, s5, 5
	s_mov_b64 s[14:15], 0x80
	s_and_b32 s5, s5, 0x60
	s_add_i32 m0, s27, 0x18000
	v_lshl_add_u64 v[8:9], v[8:9], 0, s[14:15]
	s_lshl_b32 s2, s4, 13
	s_lshl_b32 s18, s5, 7
	s_waitcnt vmcnt(0)
	s_barrier
	global_load_lds_dwordx4 v[8:9], off
	v_lshl_add_u64 v[6:7], v[6:7], 0, s[14:15]
	s_add_i32 m0, s27, 0x1a000
	s_add_i32 s43, s27, 0x8000
	s_add_i32 s44, s27, 0xa000
	global_load_lds_dwordx4 v[6:7], off
	v_lshl_add_u64 v[2:3], v[2:3], 0, s[14:15]
	s_mov_b32 m0, s43
	s_add_u32 s16, s30, 0x80080
	global_load_lds_dwordx4 v[2:3], off
	v_lshl_add_u64 v[2:3], v[4:5], 0, s[14:15]
	s_mov_b32 m0, s44
	s_addc_u32 s17, s31, 0
	global_load_lds_dwordx4 v[2:3], off
	s_add_i32 m0, s27, 0x1c000
	v_lshl_add_u64 v[2:3], s[16:17], 0, v[134:135]
	global_load_lds_dwordx4 v[2:3], off
	v_lshl_add_u64 v[2:3], s[16:17], 0, v[130:131]
	s_add_i32 m0, s27, 0x1e000
	s_cmpk_lt_u32 s1, 0x100
	global_load_lds_dwordx4 v[2:3], off
	v_lshrrev_b32_e32 v3, 1, v12
	v_and_b32_e32 v3, 24, v3
	v_and_b32_e32 v2, 15, v12
	v_lshlrev_b32_e32 v4, 1, v3
	v_lshl_or_b32 v1, s4, 6, v2
	v_lshl_or_b32 v2, v2, 6, v4
	v_lshlrev_b32_e32 v4, 2, v12
	v_and_b32_e32 v4, 32, v4
	v_bitop3_b32 v5, v2, s2, v4 bitop3:0xde
	v_bitop3_b32 v146, v2, s18, v4 bitop3:0xde
	v_lshlrev_b32_e32 v2, 15, v15
	v_and_b32_e32 v2, 0xffff0000, v2
	v_or_b32_e32 v147, s5, v3
	v_lshl_add_u32 v2, v14, 12, v2
	v_and_b32_e32 v3, 1, v15
	v_lshl_or_b32 v2, v3, 6, v2
	v_lshl_add_u32 v138, v16, 1, v2
	v_lshlrev_b32_e32 v2, 15, v10
	v_and_b32_e32 v2, 0xffff0000, v2
	s_waitcnt vmcnt(6)
	v_lshl_add_u32 v2, v11, 12, v2
	v_and_b32_e32 v3, 1, v10
	s_cselect_b64 s[16:17], -1, 0
	v_lshl_or_b32 v2, v3, 6, v2
	s_add_i32 s5, 0, 0x10000
	s_add_i32 s45, 0, 0x14000
	s_sext_i32_i16 s48, s0
	s_ashr_i32 s4, s33, 31
	v_mov_b32_e32 v139, v135
	v_lshl_add_u32 v140, v13, 1, v2
	v_mov_b32_e32 v141, v135
	v_mov_b64_e32 v[142:143], 0xb00
	v_mov_b64_e32 v[144:145], 0xaff
	v_add_u32_e32 v153, s5, v146
	v_add_u32_e32 v154, s45, v146
	v_add_u32_e32 v155, 0, v5
	s_movk_i32 s47, 0x2c00
	s_add_u32 s50, s28, 0x80080
	s_addc_u32 s51, s29, 0
	s_add_i32 m0, s27, 0xc000
	s_nop 0
	global_load_lds_dwordx4 v136, s[50:51]
	s_barrier
	s_branch .LBB0_898

;     __host__ __device__ bool next(int i, Unit& u) const { const int L = i * G + c; if (L >= n) return false; u.pm = L; u.pn = L >> 2; return true; }
; #define PG8_STAGE(bufoff, gbase, voff) do { _Pragma("unroll") for (int _i = 0; _i < 2; ++_i) \
;         __builtin_amdgcn_global_load_lds((const unsigned*)((const char*)(gbase) + (voff)[_i]), (PG8_LAS unsigned*)(lds + (bufoff) + ldsw + _i * 8192), 16, 0, 0); } while (0)
; #define PG8_LDA(dst, b, h) do { _Pragma("unroll") for (int m = 0; m < 4; ++m) _Pragma("unroll") for (int k = 0; k < 2; ++k) dst[m][k] = *(const PG8_LAS bf16x8*)(lds + PG8_SA(b, h) + aoff + m * 2048 + k * 1024); } while (0)
; #define PG8_LDB(dst, b, h) do { _Pragma("unroll") for (int n = 0; n < 2; ++n) _Pragma("unroll") for (int k = 0; k < 2; ++k) dst[n][k] = *(const PG8_LAS bf16x8*)(lds + PG8_SB(b, h) + boff + n * 2048 + k * 1024); } while (0)
; #define PG8_WAIT_V(n) asm volatile("s_waitcnt vmcnt(" #n ")" ::: "memory")
; #define PG8_WAIT_L(n) asm volatile("s_waitcnt lgkmcnt(" #n ")" ::: "memory")
; #define PG8_BAR __builtin_amdgcn_s_barrier()
; template <class Epi, class Sched, bool ALIGN_EPI>
; __device__ __forceinline__ void gemm_phase(PG8_LAS unsigned char* lds, const Gemm g, const Sched& S, const Epi& E) {
;     ...
;         const bool has_next = S.next(ui + 1, nxt);
;         const size_t tail_ = has_next ? 0 : tailoff; const char* nA = (has_next ? (const char*)g.A + (size_t)nxt.pm * tstepA : cA) + (has_next ? 0 : tailoffA); const char* nB = (has_next ? (const char*)g.Bt + (size_t)nxt.pn * tstepB : cB) + tail_;
;         for (int t = 0; t < nt; t += 2) {
;             if constexpr (Epi::MIDK) { if (t == (nt >> 1)) E.midk(acc, cur, wr, fr); }
;             const bool last = (t == nt - 2);
;             const char* a1 = cA + (size_t)(t + 1) * kstepA;
;             const char* a2 = last ? nA : cA + (size_t)(t + 2) * kstepA; const char* b2 = last ? nB : cB + (size_t)(t + 2) * kstep;
;             const char* a3 = a2 + kstepA; const char* b3 = b2 + kstep;
;             PG8_LDB(B0, 0, 0); PG8_LDB(B1, 0, 1); PG8_SCHED; PG8_LDA(At, 0, 0); PG8_STAGE(PG8_SA(1, 1), a1 + hstepA, voffA);
;             PG8_WAIT_V(8); PG8_WAIT_L(0); PG8_BAR; PG8_MMA(0, 0, At, B0); PG8_MMA(0, 1, At, B1); PG8_BAR; PG8_SCHED;
;             PG8_LDA(At, 0, 1); PG8_STAGE(PG8_SB(0, 0), b2, voffB); PG8_STAGE(PG8_SB(0, 1), b2 + hstepB, voffB); PG8_STAGE(PG8_SA(0, 0), a2, voffA);
.LBB0_900:
	s_ashr_i32 s21, s20, 31
	s_lshl_b64 s[22:23], s[20:21], 20
	s_add_u32 s2, s68, s22
	s_addc_u32 s19, s69, s23
	s_and_b64 s[22:23], s[0:1], exec
	s_cselect_b32 s2, s2, s28
	s_cselect_b32 s19, s19, s29
	s_add_u32 s22, s2, s24
	s_addc_u32 s23, s19, s25
	s_ashr_i32 s19, s18, 31
	s_lshl_b64 s[34:35], s[18:19], 20
	s_add_u32 s2, s78, s34
	s_addc_u32 s19, s79, s35
	s_and_b64 s[34:35], s[0:1], exec
	s_cselect_b32 s2, s2, s30
	s_cselect_b32 s19, s19, s31
	s_add_u32 s24, s2, s24
	s_addc_u32 s25, s19, s25
	s_add_u32 s28, s28, 0x80080
	s_addc_u32 s29, s29, 0
	s_add_u32 s19, s30, 0x100
	v_mov_b32_e32 v2, 0
	s_addc_u32 s21, s31, 0
	s_mov_b32 s49, -2
	v_mov_b32_e32 v3, v2
	v_mov_b32_e32 v4, v2
	v_mov_b32_e32 v5, v2
	v_mov_b32_e32 v6, v2
	v_mov_b32_e32 v7, v2
	v_mov_b32_e32 v8, v2
	v_mov_b32_e32 v9, v2
	v_mov_b32_e32 v18, v2
	v_mov_b32_e32 v19, v2
	v_mov_b32_e32 v20, v2
	v_mov_b32_e32 v21, v2
	v_mov_b32_e32 v22, v2
	v_mov_b32_e32 v23, v2
	v_mov_b32_e32 v24, v2
	v_mov_b32_e32 v25, v2
	v_mov_b32_e32 v34, v2
	v_mov_b32_e32 v35, v2
	v_mov_b32_e32 v36, v2
	v_mov_b32_e32 v37, v2
	v_mov_b32_e32 v38, v2
	v_mov_b32_e32 v39, v2
	v_mov_b32_e32 v40, v2
	v_mov_b32_e32 v41, v2
	v_mov_b32_e32 v50, v2
	v_mov_b32_e32 v51, v2
	v_mov_b32_e32 v52, v2
	v_mov_b32_e32 v53, v2
	v_mov_b32_e32 v54, v2
	v_mov_b32_e32 v55, v2
	v_mov_b32_e32 v56, v2
	v_mov_b32_e32 v57, v2
	v_mov_b32_e32 v10, v2
	v_mov_b32_e32 v11, v2
	v_mov_b32_e32 v12, v2
	v_mov_b32_e32 v13, v2
	v_mov_b32_e32 v14, v2
	v_mov_b32_e32 v15, v2
	v_mov_b32_e32 v16, v2
	v_mov_b32_e32 v17, v2
	v_mov_b32_e32 v26, v2
	v_mov_b32_e32 v27, v2
	v_mov_b32_e32 v28, v2
	v_mov_b32_e32 v29, v2
	v_mov_b32_e32 v30, v2
	v_mov_b32_e32 v31, v2
	v_mov_b32_e32 v32, v2
	v_mov_b32_e32 v33, v2
	v_mov_b32_e32 v42, v2
	v_mov_b32_e32 v43, v2
	v_mov_b32_e32 v44, v2
	v_mov_b32_e32 v45, v2
	v_mov_b32_e32 v46, v2
	v_mov_b32_e32 v47, v2
	v_mov_b32_e32 v48, v2
	v_mov_b32_e32 v49, v2
	v_mov_b32_e32 v58, v2
	v_mov_b32_e32 v59, v2
	v_mov_b32_e32 v60, v2
	v_mov_b32_e32 v61, v2
	v_mov_b32_e32 v62, v2
	v_mov_b32_e32 v63, v2
	v_mov_b32_e32 v64, v2
	v_mov_b32_e32 v65, v2
	v_mov_b32_e32 v66, v2
	v_mov_b32_e32 v67, v2
	v_mov_b32_e32 v68, v2
	v_mov_b32_e32 v69, v2
	v_mov_b32_e32 v70, v2
	v_mov_b32_e32 v71, v2
	v_mov_b32_e32 v72, v2
	v_mov_b32_e32 v73, v2
	v_mov_b32_e32 v82, v2
	v_mov_b32_e32 v83, v2
	v_mov_b32_e32 v84, v2
	v_mov_b32_e32 v85, v2
	v_mov_b32_e32 v86, v2
	v_mov_b32_e32 v87, v2
	v_mov_b32_e32 v88, v2
	v_mov_b32_e32 v89, v2
	v_mov_b32_e32 v98, v2
	v_mov_b32_e32 v99, v2
	v_mov_b32_e32 v100, v2
	v_mov_b32_e32 v101, v2
	v_mov_b32_e32 v102, v2
	v_mov_b32_e32 v103, v2
	v_mov_b32_e32 v104, v2
	v_mov_b32_e32 v105, v2
	v_mov_b32_e32 v114, v2
	v_mov_b32_e32 v115, v2
	v_mov_b32_e32 v116, v2
	v_mov_b32_e32 v117, v2
	v_mov_b32_e32 v118, v2
	v_mov_b32_e32 v119, v2
	v_mov_b32_e32 v120, v2
	v_mov_b32_e32 v121, v2
	v_mov_b32_e32 v74, v2
	v_mov_b32_e32 v75, v2
	v_mov_b32_e32 v76, v2
	v_mov_b32_e32 v77, v2
	v_mov_b32_e32 v78, v2
	v_mov_b32_e32 v79, v2
	v_mov_b32_e32 v80, v2
	v_mov_b32_e32 v81, v2
	v_mov_b32_e32 v90, v2
	v_mov_b32_e32 v91, v2
	v_mov_b32_e32 v92, v2
	v_mov_b32_e32 v93, v2
	v_mov_b32_e32 v94, v2
	v_mov_b32_e32 v95, v2
	v_mov_b32_e32 v96, v2
	v_mov_b32_e32 v97, v2
	v_mov_b32_e32 v106, v2
	v_mov_b32_e32 v107, v2
	v_mov_b32_e32 v108, v2
	v_mov_b32_e32 v109, v2
	v_mov_b32_e32 v110, v2
	v_mov_b32_e32 v111, v2
	v_mov_b32_e32 v112, v2
	v_mov_b32_e32 v113, v2
	v_mov_b32_e32 v122, v2
	v_mov_b32_e32 v123, v2
	v_mov_b32_e32 v124, v2
	v_mov_b32_e32 v125, v2
	v_mov_b32_e32 v126, v2
	v_mov_b32_e32 v127, v2
	v_mov_b32_e32 v128, v2
	v_mov_b32_e32 v129, v2
	s_and_b32 s2, s3, 0xfff
	s_mov_b32 s49, 0
	s_cmp_lt_u32 s3, 0x1000
	s_cbranch_scc0 .Lp8k_B_init
	s_add_u32 s28, s30, 0x80
	s_addc_u32 s29, s31, 0
	s_mov_b64 s[50:51], s[24:25]
.Lp8k_A_loop:
	s_add_i32 m0, s2, 0x18000
	s_nop 0
	global_load_lds_dwordx4 v134, s[28:29]
	s_add_i32 m0, s2, 0x1a000
	s_nop 0
	global_load_lds_dwordx4 v130, s[28:29]
	s_add_u32 s30, s28, 0x20000
	s_addc_u32 s31, s29, 0
	s_add_i32 m0, s2, 0x19000
	s_nop 0
	global_load_lds_dwordx4 v134, s[30:31]
	s_add_i32 m0, s2, 0x1b000
	s_nop 0
	global_load_lds_dwordx4 v130, s[30:31]
	s_add_u32 s30, s28, 0x80000
	s_addc_u32 s31, s29, 0
	s_add_i32 m0, s2, 0x1c000
	s_nop 0
	global_load_lds_dwordx4 v134, s[30:31]
	s_add_i32 m0, s2, 0x1e000
	s_nop 0
	global_load_lds_dwordx4 v130, s[30:31]
	s_add_u32 s30, s28, 0xa0000
	s_addc_u32 s31, s29, 0
	s_add_i32 m0, s2, 0x1d000
	s_nop 0
	global_load_lds_dwordx4 v134, s[30:31]
	s_add_i32 m0, s2, 0x1f000
	s_nop 0
	global_load_lds_dwordx4 v130, s[30:31]
	s_add_u32 s28, s28, 0x80
	s_addc_u32 s29, s29, 0
	ds_read_b128 v[190:193], v155 offset:0
	ds_read_b128 v[194:197], v155 offset:1024
	ds_read_b128 v[198:201], v155 offset:2048
	ds_read_b128 v[202:205], v155 offset:3072
	ds_read_b128 v[206:209], v155 offset:4096
	ds_read_b128 v[210:213], v155 offset:5120
	ds_read_b128 v[214:217], v155 offset:6144
	ds_read_b128 v[218:221], v155 offset:7168
	ds_read_b128 v[156:159], v153 offset:0
	ds_read_b128 v[160:163], v153 offset:1024
	ds_read_b128 v[164:167], v153 offset:2048
	ds_read_b128 v[168:171], v153 offset:3072
	ds_read_b128 v[174:177], v153 offset:16384
	ds_read_b128 v[178:181], v153 offset:17408
	ds_read_b128 v[182:185], v153 offset:18432
	ds_read_b128 v[186:189], v153 offset:19456
	ds_read_b128 v[222:225], v155 offset:16384
	ds_read_b128 v[226:229], v155 offset:17408
	ds_read_b128 v[230:233], v155 offset:18432
	ds_read_b128 v[234:237], v155 offset:19456
	ds_read_b128 v[238:241], v155 offset:20480
	ds_read_b128 v[242:245], v155 offset:21504
	ds_read_b128 v[246:249], v155 offset:22528
	ds_read_b128 v[250:253], v155 offset:23552
	s_waitcnt vmcnt(8) lgkmcnt(0)
	s_barrier
; #define PG8_STAGE(bufoff, gbase, voff) do { _Pragma("unroll") for (int _i = 0; _i < 2; ++_i) \
;         __builtin_amdgcn_global_load_lds((const unsigned*)((const char*)(gbase) + (voff)[_i]), (PG8_LAS unsigned*)(lds + (bufoff) + ldsw + _i * 8192), 16, 0, 0); } while (0)
; #define PG8_LDA(dst, b, h) do { _Pragma("unroll") for (int m = 0; m < 4; ++m) _Pragma("unroll") for (int k = 0; k < 2; ++k) dst[m][k] = *(const PG8_LAS bf16x8*)(lds + PG8_SA(b, h) + aoff + m * 2048 + k * 1024); } while (0)
; #define PG8_MMA(ai, bj, At, Bt) do { __builtin_amdgcn_s_setprio(1); _Pragma("unroll") for (int m = 0; m < 4; ++m) _Pragma("unroll") for (int n = 0; n < 2; ++n) _Pragma("unroll") for (int k = 0; k < 2; ++k) \
;         acc[ai][bj][m][n] = __builtin_amdgcn_mfma_f32_16x16x32_bf16(Bt[n][k], At[m][k], acc[ai][bj][m][n], 0, 0, 0); __builtin_amdgcn_s_setprio(0); } while (0)
; #define PG8_WAIT_V(n) asm volatile("s_waitcnt vmcnt(" #n ")" ::: "memory")
; #define PG8_WAIT_L(n) asm volatile("s_waitcnt lgkmcnt(" #n ")" ::: "memory")
; #define PG8_BAR __builtin_amdgcn_s_barrier()
; #define PG8_SCHED __builtin_amdgcn_sched_barrier(0)
; template <class Epi, class Sched, bool ALIGN_EPI>
; __device__ __forceinline__ void gemm_phase(PG8_LAS unsigned char* lds, const Gemm g, const Sched& S, const Epi& E) {
;     ...
;             PG8_WAIT_V(8); PG8_WAIT_L(0); PG8_BAR; PG8_MMA(0, 0, At, B0); PG8_MMA(0, 1, At, B1); PG8_BAR; PG8_SCHED;
;             PG8_LDA(At, 0, 1); PG8_STAGE(PG8_SB(0, 0), b2, voffB); PG8_STAGE(PG8_SB(0, 1), b2 + hstepB, voffB); PG8_STAGE(PG8_SA(0, 0), a2, voffA);
;             PG8_WAIT_V(8); PG8_WAIT_L(0); PG8_BAR; PG8_MMA(1, 0, At, B0); PG8_MMA(1, 1, At, B1); PG8_BAR; PG8_SCHED;
	s_setprio 1
	v_mfma_f32_16x16x32_bf16 v[126:129], v[156:159], v[190:193], v[126:129]
	v_mfma_f32_16x16x32_bf16 v[122:125], v[164:167], v[190:193], v[122:125]
	v_mfma_f32_16x16x32_bf16 v[110:113], v[156:159], v[198:201], v[110:113]
	v_mfma_f32_16x16x32_bf16 v[106:109], v[164:167], v[198:201], v[106:109]
	v_mfma_f32_16x16x32_bf16 v[94:97], v[156:159], v[206:209], v[94:97]
	v_mfma_f32_16x16x32_bf16 v[90:93], v[164:167], v[206:209], v[90:93]
	v_mfma_f32_16x16x32_bf16 v[78:81], v[156:159], v[214:217], v[78:81]
	v_mfma_f32_16x16x32_bf16 v[74:77], v[164:167], v[214:217], v[74:77]
	v_mfma_f32_16x16x32_bf16 v[126:129], v[160:163], v[194:197], v[126:129]
	v_mfma_f32_16x16x32_bf16 v[122:125], v[168:171], v[194:197], v[122:125]
	v_mfma_f32_16x16x32_bf16 v[110:113], v[160:163], v[202:205], v[110:113]
	v_mfma_f32_16x16x32_bf16 v[106:109], v[168:171], v[202:205], v[106:109]
	v_mfma_f32_16x16x32_bf16 v[94:97], v[160:163], v[210:213], v[94:97]
	v_mfma_f32_16x16x32_bf16 v[90:93], v[168:171], v[210:213], v[90:93]
	v_mfma_f32_16x16x32_bf16 v[78:81], v[160:163], v[218:221], v[78:81]
	v_mfma_f32_16x16x32_bf16 v[74:77], v[168:171], v[218:221], v[74:77]
	v_mfma_f32_16x16x32_bf16 v[118:121], v[174:177], v[190:193], v[118:121]
	v_mfma_f32_16x16x32_bf16 v[114:117], v[182:185], v[190:193], v[114:117]
	v_mfma_f32_16x16x32_bf16 v[102:105], v[174:177], v[198:201], v[102:105]
	v_mfma_f32_16x16x32_bf16 v[98:101], v[182:185], v[198:201], v[98:101]
	v_mfma_f32_16x16x32_bf16 v[86:89], v[174:177], v[206:209], v[86:89]
	v_mfma_f32_16x16x32_bf16 v[82:85], v[182:185], v[206:209], v[82:85]
	v_mfma_f32_16x16x32_bf16 v[70:73], v[174:177], v[214:217], v[70:73]
	v_mfma_f32_16x16x32_bf16 v[66:69], v[182:185], v[214:217], v[66:69]
	v_mfma_f32_16x16x32_bf16 v[118:121], v[178:181], v[194:197], v[118:121]
	v_mfma_f32_16x16x32_bf16 v[114:117], v[186:189], v[194:197], v[114:117]
	v_mfma_f32_16x16x32_bf16 v[102:105], v[178:181], v[202:205], v[102:105]
	v_mfma_f32_16x16x32_bf16 v[98:101], v[186:189], v[202:205], v[98:101]
	v_mfma_f32_16x16x32_bf16 v[86:89], v[178:181], v[210:213], v[86:89]
	v_mfma_f32_16x16x32_bf16 v[82:85], v[186:189], v[210:213], v[82:85]
	v_mfma_f32_16x16x32_bf16 v[70:73], v[178:181], v[218:221], v[70:73]
	v_mfma_f32_16x16x32_bf16 v[66:69], v[186:189], v[218:221], v[66:69]
	v_mfma_f32_16x16x32_bf16 v[62:65], v[156:159], v[222:225], v[62:65]
	v_mfma_f32_16x16x32_bf16 v[58:61], v[164:167], v[222:225], v[58:61]
	v_mfma_f32_16x16x32_bf16 v[46:49], v[156:159], v[230:233], v[46:49]
	v_mfma_f32_16x16x32_bf16 v[42:45], v[164:167], v[230:233], v[42:45]
	v_mfma_f32_16x16x32_bf16 v[30:33], v[156:159], v[238:241], v[30:33]
	v_mfma_f32_16x16x32_bf16 v[26:29], v[164:167], v[238:241], v[26:29]
	v_mfma_f32_16x16x32_bf16 v[14:17], v[156:159], v[246:249], v[14:17]
	v_mfma_f32_16x16x32_bf16 v[10:13], v[164:167], v[246:249], v[10:13]
	v_mfma_f32_16x16x32_bf16 v[62:65], v[160:163], v[226:229], v[62:65]
	v_mfma_f32_16x16x32_bf16 v[58:61], v[168:171], v[226:229], v[58:61]
	v_mfma_f32_16x16x32_bf16 v[46:49], v[160:163], v[234:237], v[46:49]
	v_mfma_f32_16x16x32_bf16 v[42:45], v[168:171], v[234:237], v[42:45]
	v_mfma_f32_16x16x32_bf16 v[30:33], v[160:163], v[242:245], v[30:33]
	v_mfma_f32_16x16x32_bf16 v[26:29], v[168:171], v[242:245], v[26:29]
	v_mfma_f32_16x16x32_bf16 v[14:17], v[160:163], v[250:253], v[14:17]
	v_mfma_f32_16x16x32_bf16 v[10:13], v[168:171], v[250:253], v[10:13]
	v_mfma_f32_16x16x32_bf16 v[54:57], v[174:177], v[222:225], v[54:57]
	v_mfma_f32_16x16x32_bf16 v[50:53], v[182:185], v[222:225], v[50:53]
	v_mfma_f32_16x16x32_bf16 v[38:41], v[174:177], v[230:233], v[38:41]
	v_mfma_f32_16x16x32_bf16 v[34:37], v[182:185], v[230:233], v[34:37]
	v_mfma_f32_16x16x32_bf16 v[22:25], v[174:177], v[238:241], v[22:25]
	v_mfma_f32_16x16x32_bf16 v[18:21], v[182:185], v[238:241], v[18:21]
	v_mfma_f32_16x16x32_bf16 v[6:9], v[174:177], v[246:249], v[6:9]
	v_mfma_f32_16x16x32_bf16 v[2:5], v[182:185], v[246:249], v[2:5]
	v_mfma_f32_16x16x32_bf16 v[54:57], v[178:181], v[226:229], v[54:57]
	v_mfma_f32_16x16x32_bf16 v[50:53], v[186:189], v[226:229], v[50:53]
	v_mfma_f32_16x16x32_bf16 v[38:41], v[178:181], v[234:237], v[38:41]
	v_mfma_f32_16x16x32_bf16 v[34:37], v[186:189], v[234:237], v[34:37]
	v_mfma_f32_16x16x32_bf16 v[22:25], v[178:181], v[242:245], v[22:25]
	v_mfma_f32_16x16x32_bf16 v[18:21], v[186:189], v[242:245], v[18:21]
	v_mfma_f32_16x16x32_bf16 v[6:9], v[178:181], v[250:253], v[6:9]
	v_mfma_f32_16x16x32_bf16 v[2:5], v[186:189], v[250:253], v[2:5]
	s_setprio 0
	s_waitcnt vmcnt(0)
	s_barrier
	s_cmp_eq_u32 s49, 15
	s_cselect_b32 s28, s50, s28
	s_cselect_b32 s29, s51, s29
	s_add_i32 m0, s2, 0x10000
	s_nop 0
	global_load_lds_dwordx4 v134, s[28:29]
	s_add_i32 m0, s2, 0x12000
	s_nop 0
	global_load_lds_dwordx4 v130, s[28:29]
	s_add_u32 s30, s28, 0x20000
	s_addc_u32 s31, s29, 0
	s_add_i32 m0, s2, 0x11000
	s_nop 0
	global_load_lds_dwordx4 v134, s[30:31]
	s_add_i32 m0, s2, 0x13000
	s_nop 0
	global_load_lds_dwordx4 v130, s[30:31]
	s_add_u32 s30, s28, 0x80000
	s_addc_u32 s31, s29, 0
	s_add_i32 m0, s2, 0x14000
	s_nop 0
	global_load_lds_dwordx4 v134, s[30:31]
	s_add_i32 m0, s2, 0x16000
	s_nop 0
	global_load_lds_dwordx4 v130, s[30:31]
	s_add_u32 s30, s28, 0xa0000
	s_addc_u32 s31, s29, 0
	s_add_i32 m0, s2, 0x15000
	s_nop 0
	global_load_lds_dwordx4 v134, s[30:31]
	s_add_i32 m0, s2, 0x17000
	s_nop 0
	global_load_lds_dwordx4 v130, s[30:31]
	s_add_u32 s28, s28, 0x80
	s_addc_u32 s29, s29, 0
	ds_read_b128 v[190:193], v155 offset:32768
	ds_read_b128 v[194:197], v155 offset:33792
	ds_read_b128 v[198:201], v155 offset:34816
	ds_read_b128 v[202:205], v155 offset:35840
	ds_read_b128 v[206:209], v155 offset:36864
	ds_read_b128 v[210:213], v155 offset:37888
	ds_read_b128 v[214:217], v155 offset:38912
	ds_read_b128 v[218:221], v155 offset:39936
	ds_read_b128 v[156:159], v153 offset:32768
	ds_read_b128 v[160:163], v153 offset:33792
	ds_read_b128 v[164:167], v153 offset:34816
	ds_read_b128 v[168:171], v153 offset:35840
	ds_read_b128 v[174:177], v153 offset:49152
	ds_read_b128 v[178:181], v153 offset:50176
	ds_read_b128 v[182:185], v153 offset:51200
	ds_read_b128 v[186:189], v153 offset:52224
	ds_read_b128 v[222:225], v155 offset:49152
	ds_read_b128 v[226:229], v155 offset:50176
	ds_read_b128 v[230:233], v155 offset:51200
	ds_read_b128 v[234:237], v155 offset:52224
	ds_read_b128 v[238:241], v155 offset:53248
	ds_read_b128 v[242:245], v155 offset:54272
	ds_read_b128 v[246:249], v155 offset:55296
	ds_read_b128 v[250:253], v155 offset:56320
	s_waitcnt vmcnt(8) lgkmcnt(0)
	s_barrier
; #define PG8_STAGE(bufoff, gbase, voff) do { _Pragma("unroll") for (int _i = 0; _i < 2; ++_i) \
;         __builtin_amdgcn_global_load_lds((const unsigned*)((const char*)(gbase) + (voff)[_i]), (PG8_LAS unsigned*)(lds + (bufoff) + ldsw + _i * 8192), 16, 0, 0); } while (0)
; #define PG8_LDA(dst, b, h) do { _Pragma("unroll") for (int m = 0; m < 4; ++m) _Pragma("unroll") for (int k = 0; k < 2; ++k) dst[m][k] = *(const PG8_LAS bf16x8*)(lds + PG8_SA(b, h) + aoff + m * 2048 + k * 1024); } while (0)
; #define PG8_LDB(dst, b, h) do { _Pragma("unroll") for (int n = 0; n < 2; ++n) _Pragma("unroll") for (int k = 0; k < 2; ++k) dst[n][k] = *(const PG8_LAS bf16x8*)(lds + PG8_SB(b, h) + boff + n * 2048 + k * 1024); } while (0)
; #define PG8_MMA(ai, bj, At, Bt) do { __builtin_amdgcn_s_setprio(1); _Pragma("unroll") for (int m = 0; m < 4; ++m) _Pragma("unroll") for (int n = 0; n < 2; ++n) _Pragma("unroll") for (int k = 0; k < 2; ++k) \
;         acc[ai][bj][m][n] = __builtin_amdgcn_mfma_f32_16x16x32_bf16(Bt[n][k], At[m][k], acc[ai][bj][m][n], 0, 0, 0); __builtin_amdgcn_s_setprio(0); } while (0)
; #define PG8_WAIT_V(n) asm volatile("s_waitcnt vmcnt(" #n ")" ::: "memory")
; #define PG8_WAIT_L(n) asm volatile("s_waitcnt lgkmcnt(" #n ")" ::: "memory")
; #define PG8_BAR __builtin_amdgcn_s_barrier()
; #define PG8_SCHED __builtin_amdgcn_sched_barrier(0)
; template <class Epi, class Sched, bool ALIGN_EPI>
; __device__ __forceinline__ void gemm_phase(PG8_LAS unsigned char* lds, const Gemm g, const Sched& S, const Epi& E) {
;     ...
;             PG8_WAIT_V(8); PG8_WAIT_L(0); PG8_BAR; PG8_MMA(1, 0, At, B0); PG8_MMA(1, 1, At, B1); PG8_BAR; PG8_SCHED;
;             PG8_LDB(B0, 1, 0); PG8_LDB(B1, 1, 1); PG8_SCHED; PG8_LDA(At, 1, 0); PG8_STAGE(PG8_SA(0, 1), a2 + hstepA, voffA);
;             PG8_WAIT_V(8); PG8_WAIT_L(0); PG8_BAR; PG8_MMA(0, 0, At, B0); PG8_MMA(0, 1, At, B1); PG8_BAR; PG8_SCHED;
;             PG8_LDA(At, 1, 1); PG8_STAGE(PG8_SB(1, 0), b3, voffB); PG8_STAGE(PG8_SB(1, 1), b3 + hstepB, voffB); PG8_STAGE(PG8_SA(1, 0), a3, voffA);
;             PG8_WAIT_V(8); PG8_WAIT_L(0); PG8_BAR; PG8_MMA(1, 0, At, B0); PG8_MMA(1, 1, At, B1); PG8_BAR; PG8_SCHED;
;         }
	s_setprio 1
	v_mfma_f32_16x16x32_bf16 v[126:129], v[156:159], v[190:193], v[126:129]
	v_mfma_f32_16x16x32_bf16 v[122:125], v[164:167], v[190:193], v[122:125]
	v_mfma_f32_16x16x32_bf16 v[110:113], v[156:159], v[198:201], v[110:113]
	v_mfma_f32_16x16x32_bf16 v[106:109], v[164:167], v[198:201], v[106:109]
	v_mfma_f32_16x16x32_bf16 v[94:97], v[156:159], v[206:209], v[94:97]
	v_mfma_f32_16x16x32_bf16 v[90:93], v[164:167], v[206:209], v[90:93]
	v_mfma_f32_16x16x32_bf16 v[78:81], v[156:159], v[214:217], v[78:81]
	v_mfma_f32_16x16x32_bf16 v[74:77], v[164:167], v[214:217], v[74:77]
	v_mfma_f32_16x16x32_bf16 v[126:129], v[160:163], v[194:197], v[126:129]
	v_mfma_f32_16x16x32_bf16 v[122:125], v[168:171], v[194:197], v[122:125]
	v_mfma_f32_16x16x32_bf16 v[110:113], v[160:163], v[202:205], v[110:113]
	v_mfma_f32_16x16x32_bf16 v[106:109], v[168:171], v[202:205], v[106:109]
	v_mfma_f32_16x16x32_bf16 v[94:97], v[160:163], v[210:213], v[94:97]
	v_mfma_f32_16x16x32_bf16 v[90:93], v[168:171], v[210:213], v[90:93]
	v_mfma_f32_16x16x32_bf16 v[78:81], v[160:163], v[218:221], v[78:81]
	v_mfma_f32_16x16x32_bf16 v[74:77], v[168:171], v[218:221], v[74:77]
	v_mfma_f32_16x16x32_bf16 v[118:121], v[174:177], v[190:193], v[118:121]
	v_mfma_f32_16x16x32_bf16 v[114:117], v[182:185], v[190:193], v[114:117]
	v_mfma_f32_16x16x32_bf16 v[102:105], v[174:177], v[198:201], v[102:105]
	v_mfma_f32_16x16x32_bf16 v[98:101], v[182:185], v[198:201], v[98:101]
	v_mfma_f32_16x16x32_bf16 v[86:89], v[174:177], v[206:209], v[86:89]
	v_mfma_f32_16x16x32_bf16 v[82:85], v[182:185], v[206:209], v[82:85]
	v_mfma_f32_16x16x32_bf16 v[70:73], v[174:177], v[214:217], v[70:73]
	v_mfma_f32_16x16x32_bf16 v[66:69], v[182:185], v[214:217], v[66:69]
	v_mfma_f32_16x16x32_bf16 v[118:121], v[178:181], v[194:197], v[118:121]
	v_mfma_f32_16x16x32_bf16 v[114:117], v[186:189], v[194:197], v[114:117]
	v_mfma_f32_16x16x32_bf16 v[102:105], v[178:181], v[202:205], v[102:105]
	v_mfma_f32_16x16x32_bf16 v[98:101], v[186:189], v[202:205], v[98:101]
	v_mfma_f32_16x16x32_bf16 v[86:89], v[178:181], v[210:213], v[86:89]
	v_mfma_f32_16x16x32_bf16 v[82:85], v[186:189], v[210:213], v[82:85]
	v_mfma_f32_16x16x32_bf16 v[70:73], v[178:181], v[218:221], v[70:73]
	v_mfma_f32_16x16x32_bf16 v[66:69], v[186:189], v[218:221], v[66:69]
	v_mfma_f32_16x16x32_bf16 v[62:65], v[156:159], v[222:225], v[62:65]
	v_mfma_f32_16x16x32_bf16 v[58:61], v[164:167], v[222:225], v[58:61]
	v_mfma_f32_16x16x32_bf16 v[46:49], v[156:159], v[230:233], v[46:49]
	v_mfma_f32_16x16x32_bf16 v[42:45], v[164:167], v[230:233], v[42:45]
	v_mfma_f32_16x16x32_bf16 v[30:33], v[156:159], v[238:241], v[30:33]
	v_mfma_f32_16x16x32_bf16 v[26:29], v[164:167], v[238:241], v[26:29]
	v_mfma_f32_16x16x32_bf16 v[14:17], v[156:159], v[246:249], v[14:17]
	v_mfma_f32_16x16x32_bf16 v[10:13], v[164:167], v[246:249], v[10:13]
	v_mfma_f32_16x16x32_bf16 v[62:65], v[160:163], v[226:229], v[62:65]
	v_mfma_f32_16x16x32_bf16 v[58:61], v[168:171], v[226:229], v[58:61]
	v_mfma_f32_16x16x32_bf16 v[46:49], v[160:163], v[234:237], v[46:49]
	v_mfma_f32_16x16x32_bf16 v[42:45], v[168:171], v[234:237], v[42:45]
	v_mfma_f32_16x16x32_bf16 v[30:33], v[160:163], v[242:245], v[30:33]
	v_mfma_f32_16x16x32_bf16 v[26:29], v[168:171], v[242:245], v[26:29]
	v_mfma_f32_16x16x32_bf16 v[14:17], v[160:163], v[250:253], v[14:17]
	v_mfma_f32_16x16x32_bf16 v[10:13], v[168:171], v[250:253], v[10:13]
	v_mfma_f32_16x16x32_bf16 v[54:57], v[174:177], v[222:225], v[54:57]
	v_mfma_f32_16x16x32_bf16 v[50:53], v[182:185], v[222:225], v[50:53]
	v_mfma_f32_16x16x32_bf16 v[38:41], v[174:177], v[230:233], v[38:41]
	v_mfma_f32_16x16x32_bf16 v[34:37], v[182:185], v[230:233], v[34:37]
	v_mfma_f32_16x16x32_bf16 v[22:25], v[174:177], v[238:241], v[22:25]
	v_mfma_f32_16x16x32_bf16 v[18:21], v[182:185], v[238:241], v[18:21]
	v_mfma_f32_16x16x32_bf16 v[6:9], v[174:177], v[246:249], v[6:9]
	v_mfma_f32_16x16x32_bf16 v[2:5], v[182:185], v[246:249], v[2:5]
	v_mfma_f32_16x16x32_bf16 v[54:57], v[178:181], v[226:229], v[54:57]
	v_mfma_f32_16x16x32_bf16 v[50:53], v[186:189], v[226:229], v[50:53]
	v_mfma_f32_16x16x32_bf16 v[38:41], v[178:181], v[234:237], v[38:41]
	v_mfma_f32_16x16x32_bf16 v[34:37], v[186:189], v[234:237], v[34:37]
	v_mfma_f32_16x16x32_bf16 v[22:25], v[178:181], v[242:245], v[22:25]
	v_mfma_f32_16x16x32_bf16 v[18:21], v[186:189], v[242:245], v[18:21]
	v_mfma_f32_16x16x32_bf16 v[6:9], v[178:181], v[250:253], v[6:9]
	v_mfma_f32_16x16x32_bf16 v[2:5], v[186:189], v[250:253], v[2:5]
	s_setprio 0
	s_waitcnt vmcnt(0)
	s_barrier
	s_add_i32 s49, s49, 1
	s_cmp_lt_u32 s49, 16
	s_cbranch_scc1 .Lp8k_A_loop
	s_branch .Lp8k_done
.Lp8k_B_init:
	s_sub_u32 s28, s28, 0xa0000
	s_subb_u32 s29, s29, 0
	s_sub_u32 s50, s22, 0x20000
	s_subb_u32 s51, s23, 0
; #define PG8_STAGE(bufoff, gbase, voff) do { _Pragma("unroll") for (int _i = 0; _i < 2; ++_i) \
;         __builtin_amdgcn_global_load_lds((const unsigned*)((const char*)(gbase) + (voff)[_i]), (PG8_LAS unsigned*)(lds + (bufoff) + ldsw + _i * 8192), 16, 0, 0); } while (0)
; #define PG8_LDA(dst, b, h) do { _Pragma("unroll") for (int m = 0; m < 4; ++m) _Pragma("unroll") for (int k = 0; k < 2; ++k) dst[m][k] = *(const PG8_LAS bf16x8*)(lds + PG8_SA(b, h) + aoff + m * 2048 + k * 1024); } while (0)
; #define PG8_LDB(dst, b, h) do { _Pragma("unroll") for (int n = 0; n < 2; ++n) _Pragma("unroll") for (int k = 0; k < 2; ++k) dst[n][k] = *(const PG8_LAS bf16x8*)(lds + PG8_SB(b, h) + boff + n * 2048 + k * 1024); } while (0)
; #define PG8_MMA(ai, bj, At, Bt) do { __builtin_amdgcn_s_setprio(1); _Pragma("unroll") for (int m = 0; m < 4; ++m) _Pragma("unroll") for (int n = 0; n < 2; ++n) _Pragma("unroll") for (int k = 0; k < 2; ++k) \
;         acc[ai][bj][m][n] = __builtin_amdgcn_mfma_f32_16x16x32_bf16(Bt[n][k], At[m][k], acc[ai][bj][m][n], 0, 0, 0); __builtin_amdgcn_s_setprio(0); } while (0)
; #define PG8_WAIT_V(n) asm volatile("s_waitcnt vmcnt(" #n ")" ::: "memory")
; #define PG8_WAIT_L(n) asm volatile("s_waitcnt lgkmcnt(" #n ")" ::: "memory")
; #define PG8_BAR __builtin_amdgcn_s_barrier()
; #define PG8_SCHED __builtin_amdgcn_sched_barrier(0)
; template <class Epi, class Sched, bool ALIGN_EPI>
; __device__ __forceinline__ void gemm_phase(PG8_LAS unsigned char* lds, const Gemm g, const Sched& S, const Epi& E) {
;     ...
;             PG8_LDB(B0, 0, 0); PG8_LDB(B1, 0, 1); PG8_SCHED; PG8_LDA(At, 0, 0); PG8_STAGE(PG8_SA(1, 1), a1 + hstepA, voffA);
;             PG8_WAIT_V(8); PG8_WAIT_L(0); PG8_BAR; PG8_MMA(0, 0, At, B0); PG8_MMA(0, 1, At, B1); PG8_BAR; PG8_SCHED;
;             PG8_LDA(At, 0, 1); PG8_STAGE(PG8_SB(0, 0), b2, voffB); PG8_STAGE(PG8_SB(0, 1), b2 + hstepB, voffB); PG8_STAGE(PG8_SA(0, 0), a2, voffA);
;             PG8_WAIT_V(8); PG8_WAIT_L(0); PG8_BAR; PG8_MMA(1, 0, At, B0); PG8_MMA(1, 1, At, B1); PG8_BAR; PG8_SCHED;
.Lp8k_B_loop:
	s_add_i32 m0, s2, 0xa000
	s_nop 0
	global_load_lds_dwordx4 v132, s[28:29]
	s_add_u32 s30, s28, 0x20000
	s_addc_u32 s31, s29, 0
	s_add_i32 m0, s2, 0xb000
	s_nop 0
	global_load_lds_dwordx4 v132, s[30:31]
	s_add_u32 s30, s28, 0x80000
	s_addc_u32 s31, s29, 0
	s_add_i32 m0, s2, 0xe000
	s_nop 0
	global_load_lds_dwordx4 v132, s[30:31]
	s_add_u32 s30, s28, 0xa0000
	s_addc_u32 s31, s29, 0
	s_add_i32 m0, s2, 0xf000
	s_nop 0
	global_load_lds_dwordx4 v132, s[30:31]
	s_add_u32 s34, s28, 0x80
	s_addc_u32 s35, s29, 0
	s_cmp_eq_u32 s49, 15
	s_cselect_b32 s34, s50, s34
	s_cselect_b32 s35, s51, s35
	s_add_i32 m0, s2, 0x0
	s_nop 0
	global_load_lds_dwordx4 v136, s[34:35]
	s_add_u32 s30, s34, 0x20000
	s_addc_u32 s31, s35, 0
	s_add_i32 m0, s2, 0x1000
	s_nop 0
	global_load_lds_dwordx4 v136, s[30:31]
	s_add_u32 s30, s34, 0x80000
	s_addc_u32 s31, s35, 0
	s_add_i32 m0, s2, 0x4000
	s_nop 0
	global_load_lds_dwordx4 v136, s[30:31]
	s_add_u32 s30, s34, 0xa0000
	s_addc_u32 s31, s35, 0
	s_add_i32 m0, s2, 0x5000
	s_nop 0
	global_load_lds_dwordx4 v136, s[30:31]
	s_add_u32 s28, s28, 0x80
	s_addc_u32 s29, s29, 0
	ds_read_b128 v[190:193], v155 offset:0
	ds_read_b128 v[194:197], v155 offset:1024
	ds_read_b128 v[198:201], v155 offset:2048
	ds_read_b128 v[202:205], v155 offset:3072
	ds_read_b128 v[206:209], v155 offset:4096
	ds_read_b128 v[210:213], v155 offset:5120
	ds_read_b128 v[214:217], v155 offset:6144
	ds_read_b128 v[218:221], v155 offset:7168
	ds_read_b128 v[156:159], v153 offset:0
	ds_read_b128 v[160:163], v153 offset:1024
	ds_read_b128 v[164:167], v153 offset:2048
	ds_read_b128 v[168:171], v153 offset:3072
	ds_read_b128 v[174:177], v153 offset:16384
	ds_read_b128 v[178:181], v153 offset:17408
	ds_read_b128 v[182:185], v153 offset:18432
	ds_read_b128 v[186:189], v153 offset:19456
	ds_read_b128 v[222:225], v155 offset:16384
	ds_read_b128 v[226:229], v155 offset:17408
	ds_read_b128 v[230:233], v155 offset:18432
	ds_read_b128 v[234:237], v155 offset:19456
	ds_read_b128 v[238:241], v155 offset:20480
	ds_read_b128 v[242:245], v155 offset:21504
	ds_read_b128 v[246:249], v155 offset:22528
	ds_read_b128 v[250:253], v155 offset:23552
	s_waitcnt vmcnt(8) lgkmcnt(0)
	s_barrier
	s_setprio 1
	v_mfma_f32_16x16x32_bf16 v[126:129], v[156:159], v[190:193], v[126:129]
	v_mfma_f32_16x16x32_bf16 v[122:125], v[164:167], v[190:193], v[122:125]
	v_mfma_f32_16x16x32_bf16 v[110:113], v[156:159], v[198:201], v[110:113]
	v_mfma_f32_16x16x32_bf16 v[106:109], v[164:167], v[198:201], v[106:109]
	v_mfma_f32_16x16x32_bf16 v[94:97], v[156:159], v[206:209], v[94:97]
	v_mfma_f32_16x16x32_bf16 v[90:93], v[164:167], v[206:209], v[90:93]
	v_mfma_f32_16x16x32_bf16 v[78:81], v[156:159], v[214:217], v[78:81]
	v_mfma_f32_16x16x32_bf16 v[74:77], v[164:167], v[214:217], v[74:77]
	v_mfma_f32_16x16x32_bf16 v[126:129], v[160:163], v[194:197], v[126:129]
	v_mfma_f32_16x16x32_bf16 v[122:125], v[168:171], v[194:197], v[122:125]
	v_mfma_f32_16x16x32_bf16 v[110:113], v[160:163], v[202:205], v[110:113]
	v_mfma_f32_16x16x32_bf16 v[106:109], v[168:171], v[202:205], v[106:109]
	v_mfma_f32_16x16x32_bf16 v[94:97], v[160:163], v[210:213], v[94:97]
	v_mfma_f32_16x16x32_bf16 v[90:93], v[168:171], v[210:213], v[90:93]
	v_mfma_f32_16x16x32_bf16 v[78:81], v[160:163], v[218:221], v[78:81]
	v_mfma_f32_16x16x32_bf16 v[74:77], v[168:171], v[218:221], v[74:77]
	v_mfma_f32_16x16x32_bf16 v[118:121], v[174:177], v[190:193], v[118:121]
	v_mfma_f32_16x16x32_bf16 v[114:117], v[182:185], v[190:193], v[114:117]
	v_mfma_f32_16x16x32_bf16 v[102:105], v[174:177], v[198:201], v[102:105]
	v_mfma_f32_16x16x32_bf16 v[98:101], v[182:185], v[198:201], v[98:101]
	v_mfma_f32_16x16x32_bf16 v[86:89], v[174:177], v[206:209], v[86:89]
	v_mfma_f32_16x16x32_bf16 v[82:85], v[182:185], v[206:209], v[82:85]
	v_mfma_f32_16x16x32_bf16 v[70:73], v[174:177], v[214:217], v[70:73]
	v_mfma_f32_16x16x32_bf16 v[66:69], v[182:185], v[214:217], v[66:69]
	v_mfma_f32_16x16x32_bf16 v[118:121], v[178:181], v[194:197], v[118:121]
	v_mfma_f32_16x16x32_bf16 v[114:117], v[186:189], v[194:197], v[114:117]
	v_mfma_f32_16x16x32_bf16 v[102:105], v[178:181], v[202:205], v[102:105]
	v_mfma_f32_16x16x32_bf16 v[98:101], v[186:189], v[202:205], v[98:101]
	v_mfma_f32_16x16x32_bf16 v[86:89], v[178:181], v[210:213], v[86:89]
	v_mfma_f32_16x16x32_bf16 v[82:85], v[186:189], v[210:213], v[82:85]
	v_mfma_f32_16x16x32_bf16 v[70:73], v[178:181], v[218:221], v[70:73]
	v_mfma_f32_16x16x32_bf16 v[66:69], v[186:189], v[218:221], v[66:69]
	v_mfma_f32_16x16x32_bf16 v[62:65], v[156:159], v[222:225], v[62:65]
	v_mfma_f32_16x16x32_bf16 v[58:61], v[164:167], v[222:225], v[58:61]
	v_mfma_f32_16x16x32_bf16 v[46:49], v[156:159], v[230:233], v[46:49]
	v_mfma_f32_16x16x32_bf16 v[42:45], v[164:167], v[230:233], v[42:45]
	v_mfma_f32_16x16x32_bf16 v[30:33], v[156:159], v[238:241], v[30:33]
	v_mfma_f32_16x16x32_bf16 v[26:29], v[164:167], v[238:241], v[26:29]
	v_mfma_f32_16x16x32_bf16 v[14:17], v[156:159], v[246:249], v[14:17]
	v_mfma_f32_16x16x32_bf16 v[10:13], v[164:167], v[246:249], v[10:13]
	v_mfma_f32_16x16x32_bf16 v[62:65], v[160:163], v[226:229], v[62:65]
	v_mfma_f32_16x16x32_bf16 v[58:61], v[168:171], v[226:229], v[58:61]
	v_mfma_f32_16x16x32_bf16 v[46:49], v[160:163], v[234:237], v[46:49]
	v_mfma_f32_16x16x32_bf16 v[42:45], v[168:171], v[234:237], v[42:45]
	v_mfma_f32_16x16x32_bf16 v[30:33], v[160:163], v[242:245], v[30:33]
	v_mfma_f32_16x16x32_bf16 v[26:29], v[168:171], v[242:245], v[26:29]
	v_mfma_f32_16x16x32_bf16 v[14:17], v[160:163], v[250:253], v[14:17]
	v_mfma_f32_16x16x32_bf16 v[10:13], v[168:171], v[250:253], v[10:13]
	v_mfma_f32_16x16x32_bf16 v[54:57], v[174:177], v[222:225], v[54:57]
	v_mfma_f32_16x16x32_bf16 v[50:53], v[182:185], v[222:225], v[50:53]
	v_mfma_f32_16x16x32_bf16 v[38:41], v[174:177], v[230:233], v[38:41]
	v_mfma_f32_16x16x32_bf16 v[34:37], v[182:185], v[230:233], v[34:37]
	v_mfma_f32_16x16x32_bf16 v[22:25], v[174:177], v[238:241], v[22:25]
	v_mfma_f32_16x16x32_bf16 v[18:21], v[182:185], v[238:241], v[18:21]
	v_mfma_f32_16x16x32_bf16 v[6:9], v[174:177], v[246:249], v[6:9]
	v_mfma_f32_16x16x32_bf16 v[2:5], v[182:185], v[246:249], v[2:5]
	v_mfma_f32_16x16x32_bf16 v[54:57], v[178:181], v[226:229], v[54:57]
	v_mfma_f32_16x16x32_bf16 v[50:53], v[186:189], v[226:229], v[50:53]
	v_mfma_f32_16x16x32_bf16 v[38:41], v[178:181], v[234:237], v[38:41]
	v_mfma_f32_16x16x32_bf16 v[34:37], v[186:189], v[234:237], v[34:37]
	v_mfma_f32_16x16x32_bf16 v[22:25], v[178:181], v[242:245], v[22:25]
	v_mfma_f32_16x16x32_bf16 v[18:21], v[186:189], v[242:245], v[18:21]
	v_mfma_f32_16x16x32_bf16 v[6:9], v[178:181], v[250:253], v[6:9]
	v_mfma_f32_16x16x32_bf16 v[2:5], v[186:189], v[250:253], v[2:5]
	s_setprio 0
	s_waitcnt vmcnt(0)
	s_barrier
; #define PG8_STAGE(bufoff, gbase, voff) do { _Pragma("unroll") for (int _i = 0; _i < 2; ++_i) \
;         __builtin_amdgcn_global_load_lds((const unsigned*)((const char*)(gbase) + (voff)[_i]), (PG8_LAS unsigned*)(lds + (bufoff) + ldsw + _i * 8192), 16, 0, 0); } while (0)
; #define PG8_LDA(dst, b, h) do { _Pragma("unroll") for (int m = 0; m < 4; ++m) _Pragma("unroll") for (int k = 0; k < 2; ++k) dst[m][k] = *(const PG8_LAS bf16x8*)(lds + PG8_SA(b, h) + aoff + m * 2048 + k * 1024); } while (0)
; #define PG8_LDB(dst, b, h) do { _Pragma("unroll") for (int n = 0; n < 2; ++n) _Pragma("unroll") for (int k = 0; k < 2; ++k) dst[n][k] = *(const PG8_LAS bf16x8*)(lds + PG8_SB(b, h) + boff + n * 2048 + k * 1024); } while (0)
; #define PG8_MMA(ai, bj, At, Bt) do { __builtin_amdgcn_s_setprio(1); _Pragma("unroll") for (int m = 0; m < 4; ++m) _Pragma("unroll") for (int n = 0; n < 2; ++n) _Pragma("unroll") for (int k = 0; k < 2; ++k) \
;         acc[ai][bj][m][n] = __builtin_amdgcn_mfma_f32_16x16x32_bf16(Bt[n][k], At[m][k], acc[ai][bj][m][n], 0, 0, 0); __builtin_amdgcn_s_setprio(0); } while (0)
; #define PG8_WAIT_V(n) asm volatile("s_waitcnt vmcnt(" #n ")" ::: "memory")
; #define PG8_WAIT_L(n) asm volatile("s_waitcnt lgkmcnt(" #n ")" ::: "memory")
; #define PG8_BAR __builtin_amdgcn_s_barrier()
; #define PG8_SCHED __builtin_amdgcn_sched_barrier(0)
; template <class Epi, class Sched, bool ALIGN_EPI>
; __device__ __forceinline__ void gemm_phase(PG8_LAS unsigned char* lds, const Gemm g, const Sched& S, const Epi& E) {
;     ...
;             PG8_LDB(B0, 1, 0); PG8_LDB(B1, 1, 1); PG8_SCHED; PG8_LDA(At, 1, 0); PG8_STAGE(PG8_SA(0, 1), a2 + hstepA, voffA);
;             PG8_WAIT_V(8); PG8_WAIT_L(0); PG8_BAR; PG8_MMA(0, 0, At, B0); PG8_MMA(0, 1, At, B1); PG8_BAR; PG8_SCHED;
;             PG8_LDA(At, 1, 1); PG8_STAGE(PG8_SB(1, 0), b3, voffB); PG8_STAGE(PG8_SB(1, 1), b3 + hstepB, voffB); PG8_STAGE(PG8_SA(1, 0), a3, voffA);
;             PG8_WAIT_V(8); PG8_WAIT_L(0); PG8_BAR; PG8_MMA(1, 0, At, B0); PG8_MMA(1, 1, At, B1); PG8_BAR; PG8_SCHED;
;         }
	s_cmp_eq_u32 s49, 15
	s_cselect_b32 s28, s50, s28
	s_cselect_b32 s29, s51, s29
	s_add_i32 m0, s2, 0x2000
	s_nop 0
	global_load_lds_dwordx4 v132, s[28:29]
	s_add_u32 s30, s28, 0x20000
	s_addc_u32 s31, s29, 0
	s_add_i32 m0, s2, 0x3000
	s_nop 0
	global_load_lds_dwordx4 v132, s[30:31]
	s_add_u32 s30, s28, 0x80000
	s_addc_u32 s31, s29, 0
	s_add_i32 m0, s2, 0x6000
	s_nop 0
	global_load_lds_dwordx4 v132, s[30:31]
	s_add_u32 s30, s28, 0xa0000
	s_addc_u32 s31, s29, 0
	s_add_i32 m0, s2, 0x7000
	s_nop 0
	global_load_lds_dwordx4 v132, s[30:31]
	s_add_u32 s34, s28, 0x80
	s_addc_u32 s35, s29, 0
	s_add_i32 m0, s2, 0x8000
	s_nop 0
	global_load_lds_dwordx4 v136, s[34:35]
	s_add_u32 s30, s34, 0x20000
	s_addc_u32 s31, s35, 0
	s_add_i32 m0, s2, 0x9000
	s_nop 0
	global_load_lds_dwordx4 v136, s[30:31]
	s_add_u32 s30, s34, 0x80000
	s_addc_u32 s31, s35, 0
	s_add_i32 m0, s2, 0xc000
	s_nop 0
	global_load_lds_dwordx4 v136, s[30:31]
	s_add_u32 s30, s34, 0xa0000
	s_addc_u32 s31, s35, 0
	s_add_i32 m0, s2, 0xd000
	s_nop 0
	global_load_lds_dwordx4 v136, s[30:31]
	s_add_u32 s28, s28, 0x80
	s_addc_u32 s29, s29, 0
	ds_read_b128 v[190:193], v155 offset:32768
	ds_read_b128 v[194:197], v155 offset:33792
	ds_read_b128 v[198:201], v155 offset:34816
	ds_read_b128 v[202:205], v155 offset:35840
	ds_read_b128 v[206:209], v155 offset:36864
	ds_read_b128 v[210:213], v155 offset:37888
	ds_read_b128 v[214:217], v155 offset:38912
	ds_read_b128 v[218:221], v155 offset:39936
	ds_read_b128 v[156:159], v153 offset:32768
	ds_read_b128 v[160:163], v153 offset:33792
	ds_read_b128 v[164:167], v153 offset:34816
	ds_read_b128 v[168:171], v153 offset:35840
	ds_read_b128 v[174:177], v153 offset:49152
	ds_read_b128 v[178:181], v153 offset:50176
	ds_read_b128 v[182:185], v153 offset:51200
	ds_read_b128 v[186:189], v153 offset:52224
	ds_read_b128 v[222:225], v155 offset:49152
	ds_read_b128 v[226:229], v155 offset:50176
	ds_read_b128 v[230:233], v155 offset:51200
	ds_read_b128 v[234:237], v155 offset:52224
	ds_read_b128 v[238:241], v155 offset:53248
	ds_read_b128 v[242:245], v155 offset:54272
	ds_read_b128 v[246:249], v155 offset:55296
	ds_read_b128 v[250:253], v155 offset:56320
	s_waitcnt vmcnt(8) lgkmcnt(0)
	s_barrier
	s_setprio 1
	v_mfma_f32_16x16x32_bf16 v[126:129], v[156:159], v[190:193], v[126:129]
	v_mfma_f32_16x16x32_bf16 v[122:125], v[164:167], v[190:193], v[122:125]
	v_mfma_f32_16x16x32_bf16 v[110:113], v[156:159], v[198:201], v[110:113]
	v_mfma_f32_16x16x32_bf16 v[106:109], v[164:167], v[198:201], v[106:109]
	v_mfma_f32_16x16x32_bf16 v[94:97], v[156:159], v[206:209], v[94:97]
	v_mfma_f32_16x16x32_bf16 v[90:93], v[164:167], v[206:209], v[90:93]
	v_mfma_f32_16x16x32_bf16 v[78:81], v[156:159], v[214:217], v[78:81]
	v_mfma_f32_16x16x32_bf16 v[74:77], v[164:167], v[214:217], v[74:77]
	v_mfma_f32_16x16x32_bf16 v[126:129], v[160:163], v[194:197], v[126:129]
	v_mfma_f32_16x16x32_bf16 v[122:125], v[168:171], v[194:197], v[122:125]
	v_mfma_f32_16x16x32_bf16 v[110:113], v[160:163], v[202:205], v[110:113]
	v_mfma_f32_16x16x32_bf16 v[106:109], v[168:171], v[202:205], v[106:109]
	v_mfma_f32_16x16x32_bf16 v[94:97], v[160:163], v[210:213], v[94:97]
	v_mfma_f32_16x16x32_bf16 v[90:93], v[168:171], v[210:213], v[90:93]
	v_mfma_f32_16x16x32_bf16 v[78:81], v[160:163], v[218:221], v[78:81]
	v_mfma_f32_16x16x32_bf16 v[74:77], v[168:171], v[218:221], v[74:77]
	v_mfma_f32_16x16x32_bf16 v[118:121], v[174:177], v[190:193], v[118:121]
	v_mfma_f32_16x16x32_bf16 v[114:117], v[182:185], v[190:193], v[114:117]
	v_mfma_f32_16x16x32_bf16 v[102:105], v[174:177], v[198:201], v[102:105]
	v_mfma_f32_16x16x32_bf16 v[98:101], v[182:185], v[198:201], v[98:101]
	v_mfma_f32_16x16x32_bf16 v[86:89], v[174:177], v[206:209], v[86:89]
	v_mfma_f32_16x16x32_bf16 v[82:85], v[182:185], v[206:209], v[82:85]
	v_mfma_f32_16x16x32_bf16 v[70:73], v[174:177], v[214:217], v[70:73]
	v_mfma_f32_16x16x32_bf16 v[66:69], v[182:185], v[214:217], v[66:69]
	v_mfma_f32_16x16x32_bf16 v[118:121], v[178:181], v[194:197], v[118:121]
	v_mfma_f32_16x16x32_bf16 v[114:117], v[186:189], v[194:197], v[114:117]
	v_mfma_f32_16x16x32_bf16 v[102:105], v[178:181], v[202:205], v[102:105]
	v_mfma_f32_16x16x32_bf16 v[98:101], v[186:189], v[202:205], v[98:101]
	v_mfma_f32_16x16x32_bf16 v[86:89], v[178:181], v[210:213], v[86:89]
	v_mfma_f32_16x16x32_bf16 v[82:85], v[186:189], v[210:213], v[82:85]
	v_mfma_f32_16x16x32_bf16 v[70:73], v[178:181], v[218:221], v[70:73]
	v_mfma_f32_16x16x32_bf16 v[66:69], v[186:189], v[218:221], v[66:69]
	v_mfma_f32_16x16x32_bf16 v[62:65], v[156:159], v[222:225], v[62:65]
	v_mfma_f32_16x16x32_bf16 v[58:61], v[164:167], v[222:225], v[58:61]
	v_mfma_f32_16x16x32_bf16 v[46:49], v[156:159], v[230:233], v[46:49]
	v_mfma_f32_16x16x32_bf16 v[42:45], v[164:167], v[230:233], v[42:45]
	v_mfma_f32_16x16x32_bf16 v[30:33], v[156:159], v[238:241], v[30:33]
	v_mfma_f32_16x16x32_bf16 v[26:29], v[164:167], v[238:241], v[26:29]
	v_mfma_f32_16x16x32_bf16 v[14:17], v[156:159], v[246:249], v[14:17]
	v_mfma_f32_16x16x32_bf16 v[10:13], v[164:167], v[246:249], v[10:13]
	v_mfma_f32_16x16x32_bf16 v[62:65], v[160:163], v[226:229], v[62:65]
	v_mfma_f32_16x16x32_bf16 v[58:61], v[168:171], v[226:229], v[58:61]
	v_mfma_f32_16x16x32_bf16 v[46:49], v[160:163], v[234:237], v[46:49]
	v_mfma_f32_16x16x32_bf16 v[42:45], v[168:171], v[234:237], v[42:45]
	v_mfma_f32_16x16x32_bf16 v[30:33], v[160:163], v[242:245], v[30:33]
	v_mfma_f32_16x16x32_bf16 v[26:29], v[168:171], v[242:245], v[26:29]
	v_mfma_f32_16x16x32_bf16 v[14:17], v[160:163], v[250:253], v[14:17]
	v_mfma_f32_16x16x32_bf16 v[10:13], v[168:171], v[250:253], v[10:13]
	v_mfma_f32_16x16x32_bf16 v[54:57], v[174:177], v[222:225], v[54:57]
	v_mfma_f32_16x16x32_bf16 v[50:53], v[182:185], v[222:225], v[50:53]
	v_mfma_f32_16x16x32_bf16 v[38:41], v[174:177], v[230:233], v[38:41]
	v_mfma_f32_16x16x32_bf16 v[34:37], v[182:185], v[230:233], v[34:37]
	v_mfma_f32_16x16x32_bf16 v[22:25], v[174:177], v[238:241], v[22:25]
	v_mfma_f32_16x16x32_bf16 v[18:21], v[182:185], v[238:241], v[18:21]
	v_mfma_f32_16x16x32_bf16 v[6:9], v[174:177], v[246:249], v[6:9]
	v_mfma_f32_16x16x32_bf16 v[2:5], v[182:185], v[246:249], v[2:5]
	v_mfma_f32_16x16x32_bf16 v[54:57], v[178:181], v[226:229], v[54:57]
	v_mfma_f32_16x16x32_bf16 v[50:53], v[186:189], v[226:229], v[50:53]
	v_mfma_f32_16x16x32_bf16 v[38:41], v[178:181], v[234:237], v[38:41]
	v_mfma_f32_16x16x32_bf16 v[34:37], v[186:189], v[234:237], v[34:37]
	v_mfma_f32_16x16x32_bf16 v[22:25], v[178:181], v[242:245], v[22:25]
	v_mfma_f32_16x16x32_bf16 v[18:21], v[186:189], v[242:245], v[18:21]
	v_mfma_f32_16x16x32_bf16 v[6:9], v[178:181], v[250:253], v[6:9]
	v_mfma_f32_16x16x32_bf16 v[2:5], v[186:189], v[250:253], v[2:5]
	s_setprio 0
	s_waitcnt vmcnt(0)
	s_barrier
	s_add_i32 s49, s49, 1
	s_cmp_lt_u32 s49, 16
	s_cbranch_scc1 .Lp8k_B_loop
.Lp8k_done:
	s_and_b64 vcc, exec, s[16:17]
	s_cbranch_vccz .LBB0_904
	s_barrier
